# k34 + attention P*V software pipelining + score-scaling de-packing combined
# baseline (speedup 1.0000x reference)
; __device__ void phase_attn(const Params& p, unsigned char* smem, int wave) {
;     ...
;         const bf16x8 qf0 = *(const bf16x8*)(Qs + (16 * w4 + ql) * ATT_LD + gq * 8), qf1 = *(const bf16x8*)(Qs + (16 * w4 + ql) * ATT_LD + 32 + gq * 8);
;         f32x4 sc[10];
; #pragma unroll
;         for (int kt = 0; kt < 9; ++kt) { const bf16_t* kr = Ks + (16 * w4 + 16 * kt + ql) * ATT_LD + gq * 8;
;             f32x4 a = (f32x4){0.f, 0.f, 0.f, 0.f};
;             a = __builtin_amdgcn_mfma_f32_16x16x32_bf16(*(const bf16x8*)kr, qf0, a, 0, 0, 0);
;             a = __builtin_amdgcn_mfma_f32_16x16x32_bf16(*(const bf16x8*)(kr + 32), qf1, a, 0, 0, 0);
;             sc[kt] = a; if (kt % 3 == 2) __builtin_amdgcn_sched_barrier(0); }
;         const float slope = exp2f(-(float)(h + 1)) * (float)d * 1.4426950408889634f;
;         const int qi = i0 + 16 * w4 + ql;
;         float mx = -1e30f;
; #pragma unroll
;         for (int kt = 0; kt < 9; ++kt)
; #pragma unroll
;             for (int j = 0; j < 4; ++j) { const int rel = 16 * kt + 4 * gq + j - 64 - ql; const int jk = qi + rel;
;                 const bool relok = (kt == 0) ? (rel >= -64) : ((kt == 8) ? (rel <= 64) : true);
;                 const bool ok = relok && ((unsigned)jk < (unsigned)Ls);
;                 const float v = ok ? sc[kt][j] * 0.18033688011112042f - slope * fabsf((float)rel) : -1e30f;
;                 sc[kt][j] = v; mx = fmaxf(mx, v); }
.LBB0_732:
	v_readlane_b32 s28, v253, 8
	v_readlane_b32 s30, v253, 10
	v_readlane_b32 s31, v253, 11
	s_add_u32 s59, s30, s20
	s_mul_i32 s18, s22, 0xfffffd80
	s_waitcnt lgkmcnt(8)
	v_mfma_f32_16x16x32_bf16 v[46:49], v[232:235], v[186:189], 0
	s_mul_i32 s19, s22, 0xfffec000
	s_addc_u32 s60, s31, s21
	s_add_i32 s18, s23, s18
	s_waitcnt lgkmcnt(6)
	v_mfma_f32_16x16x32_bf16 v[194:197], v[50:53], v[190:193], v[46:49]
	s_add_i32 s19, s48, s19
	s_and_b32 s57, s22, 7
	s_and_b32 s19, s19, 0xfffff800
	s_waitcnt lgkmcnt(5)
	v_mfma_f32_16x16x32_bf16 v[50:53], v[54:57], v[186:189], 0
	s_and_b32 s20, s18, 15
	s_add_i32 s21, s18, 0xfffffe00
	s_cmpk_lt_i32 s18, 0x200
	s_cselect_b32 s18, s20, s21
	s_cselect_b32 s20, s50, 0x4000
	s_cselect_b32 s61, s19, 0x10000
	s_cmp_eq_u32 s42, 1
	s_cselect_b32 s19, 4, 16
	s_cselect_b32 s21, 2, 4
	s_cmp_lt_u32 s22, 8
	s_waitcnt lgkmcnt(3)
	v_mfma_f32_16x16x32_bf16 v[46:49], v[236:239], v[186:189], 0
	s_cselect_b32 s22, 1, s19
	s_cselect_b32 s58, 0, s21
	s_add_i32 s19, s22, -1
	s_lshr_b32 s63, s20, s58
	s_and_b32 s62, s19, s18
	s_lshr_b32 s20, s18, s58
	v_readlane_b32 s29, v253, 9
	v_mfma_f32_16x16x32_bf16 v[198:201], v[58:61], v[190:193], v[50:53]
	s_waitcnt lgkmcnt(2)
	v_mfma_f32_16x16x32_bf16 v[202:205], v[240:243], v[190:193], v[46:49]
	s_nop 2
	ds_read_b128 v[54:57], v140 offset:27648
	ds_read_b128 v[58:61], v140 offset:27712
	s_waitcnt lgkmcnt(3)
	v_mfma_f32_16x16x32_bf16 v[46:49], v[244:247], v[186:189], 0
	s_waitcnt lgkmcnt(2)
	v_mfma_f32_16x16x32_bf16 v[206:209], v[248:251], v[190:193], v[46:49]
	ds_read_b128 v[50:53], v140 offset:30016
	s_nop 4
	ds_read_b128 v[46:49], v140 offset:29952
	s_waitcnt lgkmcnt(3)
	v_mfma_f32_16x16x32_bf16 v[54:57], v[54:57], v[186:189], 0
	s_waitcnt lgkmcnt(0)
	v_mfma_f32_16x16x32_bf16 v[46:49], v[46:49], v[186:189], 0
	v_mfma_f32_16x16x32_bf16 v[62:65], v[58:61], v[190:193], v[54:57]
	v_mfma_f32_16x16x32_bf16 v[58:61], v[50:53], v[190:193], v[46:49]
	s_nop 5
	ds_read_b128 v[46:49], v140 offset:32256
	ds_read_b128 v[50:53], v140 offset:32320
	ds_read_b128 v[54:57], v140 offset:34560
	ds_read_b128 v[210:213], v140 offset:34624
	s_waitcnt lgkmcnt(3)
	v_mfma_f32_16x16x32_bf16 v[46:49], v[46:49], v[186:189], 0
	s_waitcnt lgkmcnt(1)
	v_mfma_f32_16x16x32_bf16 v[214:217], v[54:57], v[186:189], 0
	v_mfma_f32_16x16x32_bf16 v[54:57], v[50:53], v[190:193], v[46:49]
	s_nop 4
	ds_read_b128 v[46:49], v140 offset:36864
	s_waitcnt lgkmcnt(1)
	v_mfma_f32_16x16x32_bf16 v[50:53], v[210:213], v[190:193], v[214:217]
	ds_read_b128 v[210:213], v140 offset:36928
	s_waitcnt lgkmcnt(1)
	v_mfma_f32_16x16x32_bf16 v[46:49], v[46:49], v[186:189], 0
	s_waitcnt lgkmcnt(0)
	v_mfma_f32_16x16x32_bf16 v[46:49], v[210:213], v[190:193], v[46:49]
	s_add_i32 s18, s57, 1
	v_cvt_f32_ubyte0_e32 v12, s18
	v_cmp_lt_f32_e32 vcc, s51, v12
	s_and_b64 s[18:19], vcc, exec
	s_cselect_b32 s18, 0xffffffc0, 0
	v_cndmask_b32_e32 v13, 0, v181, vcc
	v_sub_f32_e32 v12, v13, v12
	v_exp_f32_e32 v12, v12
	v_lshl_add_u32 v139, s20, 7, v67
	v_cvt_f32_ubyte0_e32 v13, s22
	v_or_b32_e32 v45, v139, v66
	v_ldexp_f32 v12, v12, s18
	v_mul_f32_e32 v13, v12, v13
	v_add_u32_e32 v12, v45, v143
	v_cmp_gt_u32_e64 s[26:27], s63, v12
	v_add_u32_e32 v12, v45, v144
	v_cmp_gt_u32_e64 s[28:29], s63, v12
	v_add_u32_e32 v12, v45, v145
	v_cmp_gt_u32_e64 s[30:31], s63, v12
	v_add_u32_e32 v12, v45, v146
	v_cmp_gt_u32_e64 s[34:35], s63, v12
	v_add_u32_e32 v12, v45, v174
	v_cmp_gt_u32_e64 s[22:23], s63, v12
	v_add_u32_e32 v12, v45, v175
	v_cmp_gt_u32_e64 s[20:21], s63, v12
	v_add_u32_e32 v12, v45, v176
	v_cmp_gt_u32_e32 vcc, s63, v12
	v_add_u32_e32 v12, v45, v177
	v_cmp_gt_u32_e64 s[18:19], s63, v12
	v_mov_b32_e32 v12, v49
	v_pk_mul_f32 v[12:13], v[12:13], s[44:45]
	v_mul_f32_e32 v186, v68, v194
	v_mul_f32_e32 v187, v69, v13
	s_and_b64 s[26:27], s[24:25], s[26:27]
	v_sub_f32_e32 v49, v186, v187
	v_mul_f32_e32 v186, v70, v195
	v_mul_f32_e32 v187, v71, v13
	v_cndmask_b32_e64 v194, v182, v49, s[26:27]
	v_sub_f32_e32 v49, v186, v187
	s_and_b64 s[26:27], s[4:5], s[28:29]
	v_mul_f32_e32 v186, v72, v196
	v_mul_f32_e32 v187, v73, v13
	v_cndmask_b32_e64 v195, v182, v49, s[26:27]
	v_sub_f32_e32 v186, v186, v187
	s_and_b64 s[26:27], s[6:7], s[30:31]
	v_cndmask_b32_e64 v196, v182, v186, s[26:27]
	v_mul_f32_e32 v186, v74, v197
	v_mul_f32_e32 v187, v75, v13
	s_and_b64 s[26:27], s[8:9], s[34:35]
	v_sub_f32_e32 v186, v186, v187
	v_cndmask_b32_e64 v197, v182, v186, s[26:27]
	v_add_u32_e32 v14, v45, v147
	v_mul_f32_e32 v186, v76, v198
	v_mul_f32_e32 v187, v77, v13
	v_cmp_gt_u32_e64 s[26:27], s63, v14
	v_sub_f32_e32 v186, v186, v187
	s_nop 0
	v_cndmask_b32_e64 v14, v182, v186, s[26:27]
	v_add_u32_e32 v188, v45, v148
	v_mul_f32_e32 v186, v78, v199
	v_mul_f32_e32 v187, v79, v13
	v_cmp_gt_u32_e64 s[26:27], s63, v188
	v_sub_f32_e32 v186, v186, v187
	s_nop 0
	v_cndmask_b32_e64 v188, v182, v186, s[26:27]
	v_add_u32_e32 v189, v45, v149
	v_mul_f32_e32 v186, v80, v200
	v_mul_f32_e32 v187, v81, v13
	v_cmp_gt_u32_e64 s[26:27], s63, v189
	v_sub_f32_e32 v186, v186, v187
	s_nop 0
	v_cndmask_b32_e64 v189, v182, v186, s[26:27]
	v_add_u32_e32 v190, v45, v150
	v_mul_f32_e32 v186, v82, v201
	v_mul_f32_e32 v187, v83, v13
	v_cmp_gt_u32_e64 s[26:27], s63, v190
	v_sub_f32_e32 v186, v186, v187
	s_nop 0
	v_cndmask_b32_e64 v190, v182, v186, s[26:27]
	v_add_u32_e32 v191, v45, v151
	v_mul_f32_e32 v186, v84, v202
	v_mul_f32_e32 v187, v85, v13
	v_cmp_gt_u32_e64 s[26:27], s63, v191
	v_sub_f32_e32 v186, v186, v187
	s_nop 0
	v_cndmask_b32_e64 v191, v182, v186, s[26:27]
	v_add_u32_e32 v192, v45, v152
	v_mul_f32_e32 v186, v86, v203
	v_mul_f32_e32 v187, v87, v13
	v_cmp_gt_u32_e64 s[26:27], s63, v192
	v_sub_f32_e32 v186, v186, v187
; __device__ void phase_attn(const Params& p, unsigned char* smem, int wave) {
;     ...
;         const float slope = exp2f(-(float)(h + 1)) * (float)d * 1.4426950408889634f;
;         const int qi = i0 + 16 * w4 + ql;
;         float mx = -1e30f;
; #pragma unroll
;         for (int kt = 0; kt < 9; ++kt)
; #pragma unroll
;             for (int j = 0; j < 4; ++j) { const int rel = 16 * kt + 4 * gq + j - 64 - ql; const int jk = qi + rel;
;                 const bool relok = (kt == 0) ? (rel >= -64) : ((kt == 8) ? (rel <= 64) : true);
;                 const bool ok = relok && ((unsigned)jk < (unsigned)Ls);
;                 const float v = ok ? sc[kt][j] * 0.18033688011112042f - slope * fabsf((float)rel) : -1e30f;
;                 sc[kt][j] = v; mx = fmaxf(mx, v); }
;         mx = fmaxf(mx, __shfl_xor(mx, 16)); mx = fmaxf(mx, __shfl_xor(mx, 32));
	s_nop 0
	v_cndmask_b32_e64 v192, v182, v186, s[26:27]
	v_add_u32_e32 v193, v45, v153
	v_mul_f32_e32 v186, v88, v204
	v_mul_f32_e32 v187, v89, v13
	v_cmp_gt_u32_e64 s[26:27], s63, v193
	v_sub_f32_e32 v186, v186, v187
	s_nop 0
	v_cndmask_b32_e64 v193, v182, v186, s[26:27]
	v_add_u32_e32 v210, v45, v154
	v_mul_f32_e32 v186, v90, v205
	v_mul_f32_e32 v187, v91, v13
	v_cmp_gt_u32_e64 s[26:27], s63, v210
	v_sub_f32_e32 v186, v186, v187
	s_nop 0
	v_cndmask_b32_e64 v198, v182, v186, s[26:27]
	v_add_u32_e32 v211, v45, v155
	v_mul_f32_e32 v186, v92, v206
	v_mul_f32_e32 v187, v93, v13
	v_cmp_gt_u32_e64 s[26:27], s63, v211
	v_sub_f32_e32 v186, v186, v187
	s_nop 0
	v_cndmask_b32_e64 v199, v182, v186, s[26:27]
	v_add_u32_e32 v212, v45, v156
	v_mul_f32_e32 v186, v94, v207
	v_mul_f32_e32 v187, v95, v13
	v_cmp_gt_u32_e64 s[26:27], s63, v212
	v_sub_f32_e32 v186, v186, v187
	s_nop 0
	v_cndmask_b32_e64 v200, v182, v186, s[26:27]
	v_add_u32_e32 v213, v45, v157
	v_mul_f32_e32 v186, v96, v208
	v_mul_f32_e32 v187, v97, v13
	v_cmp_gt_u32_e64 s[26:27], s63, v213
	v_sub_f32_e32 v186, v186, v187
	s_nop 0
	v_cndmask_b32_e64 v201, v182, v186, s[26:27]
	v_add_u32_e32 v214, v45, v158
	v_mul_f32_e32 v186, v98, v209
	v_mul_f32_e32 v187, v99, v13
	v_cmp_gt_u32_e64 s[26:27], s63, v214
	v_sub_f32_e32 v186, v186, v187
	s_nop 0
	v_cndmask_b32_e64 v202, v182, v186, s[26:27]
	v_add_u32_e32 v215, v45, v142
	v_mul_f32_e32 v186, v100, v62
	v_mul_f32_e32 v187, v101, v13
	v_cmp_gt_u32_e64 s[26:27], s63, v215
	v_sub_f32_e32 v62, v186, v187
	v_add_u32_e32 v216, v45, v159
	v_cndmask_b32_e64 v186, v182, v62, s[26:27]
	v_mul_f32_e32 v62, v102, v63
	v_mul_f32_e32 v63, v103, v13
	v_cmp_gt_u32_e64 s[26:27], s63, v216
	v_sub_f32_e32 v62, v62, v63
	s_nop 0
	v_cndmask_b32_e64 v187, v182, v62, s[26:27]
	v_add_u32_e32 v217, v45, v160
	v_mul_f32_e32 v62, v104, v64
	v_mul_f32_e32 v63, v105, v13
	v_cmp_gt_u32_e64 s[26:27], s63, v217
	v_sub_f32_e32 v62, v62, v63
	s_nop 0
	v_cndmask_b32_e64 v64, v182, v62, s[26:27]
	v_add_u32_e32 v218, v45, v161
	v_mul_f32_e32 v62, v106, v65
	v_mul_f32_e32 v63, v107, v13
	v_cmp_gt_u32_e64 s[26:27], s63, v218
	v_sub_f32_e32 v62, v62, v63
	s_nop 0
	v_cndmask_b32_e64 v65, v182, v62, s[26:27]
	v_add_u32_e32 v219, v45, v162
	v_mul_f32_e32 v62, v108, v58
	v_mul_f32_e32 v63, v109, v13
	v_cmp_gt_u32_e64 s[26:27], s63, v219
	v_sub_f32_e32 v58, v62, v63
	v_add_u32_e32 v220, v45, v163
	v_cndmask_b32_e64 v62, v182, v58, s[26:27]
	v_mul_f32_e32 v58, v110, v59
	v_mul_f32_e32 v59, v111, v13
	v_cmp_gt_u32_e64 s[26:27], s63, v220
	v_sub_f32_e32 v58, v58, v59
	s_nop 0
	v_cndmask_b32_e64 v63, v182, v58, s[26:27]
	v_add_u32_e32 v221, v45, v164
	v_mul_f32_e32 v58, v112, v60
	v_mul_f32_e32 v59, v113, v13
	v_cmp_gt_u32_e64 s[26:27], s63, v221
	v_sub_f32_e32 v58, v58, v59
	s_nop 0
	v_cndmask_b32_e64 v60, v182, v58, s[26:27]
	v_add_u32_e32 v222, v45, v165
	v_mul_f32_e32 v58, v114, v61
	v_mul_f32_e32 v59, v115, v13
	v_cmp_gt_u32_e64 s[26:27], s63, v222
	v_sub_f32_e32 v58, v58, v59
	s_nop 0
	v_cndmask_b32_e64 v61, v182, v58, s[26:27]
	v_add_u32_e32 v223, v45, v166
	v_mul_f32_e32 v58, v116, v54
	v_mul_f32_e32 v59, v117, v13
	v_cmp_gt_u32_e64 s[26:27], s63, v223
	v_sub_f32_e32 v54, v58, v59
	v_add_u32_e32 v224, v45, v167
	v_cndmask_b32_e64 v58, v182, v54, s[26:27]
	v_mul_f32_e32 v54, v118, v55
	v_mul_f32_e32 v55, v119, v13
	v_cmp_gt_u32_e64 s[26:27], s63, v224
	v_sub_f32_e32 v54, v54, v55
	s_nop 0
	v_cndmask_b32_e64 v59, v182, v54, s[26:27]
	v_add_u32_e32 v225, v45, v168
	v_mul_f32_e32 v54, v120, v56
	v_mul_f32_e32 v55, v121, v13
	v_cmp_gt_u32_e64 s[26:27], s63, v225
	v_sub_f32_e32 v54, v54, v55
	s_nop 0
	v_cndmask_b32_e64 v56, v182, v54, s[26:27]
	v_add_u32_e32 v226, v45, v169
	v_mul_f32_e32 v54, v122, v57
	v_mul_f32_e32 v55, v123, v13
	v_cmp_gt_u32_e64 s[26:27], s63, v226
	v_sub_f32_e32 v54, v54, v55
	s_nop 0
	v_cndmask_b32_e64 v57, v182, v54, s[26:27]
	v_add_u32_e32 v227, v45, v170
	v_mul_f32_e32 v54, v124, v50
	v_mul_f32_e32 v55, v125, v13
	v_cmp_gt_u32_e64 s[26:27], s63, v227
	v_sub_f32_e32 v50, v54, v55
	v_max3_f32 v49, v194, s52, v195
	v_cndmask_b32_e64 v54, v182, v50, s[26:27]
	v_add_u32_e32 v228, v45, v171
	v_max3_f32 v49, v49, v196, v197
	v_mul_f32_e32 v50, v126, v51
	v_mul_f32_e32 v51, v127, v13
	v_max3_f32 v49, v49, v14, v188
	v_sub_f32_e32 v50, v50, v51
	v_cmp_gt_u32_e64 s[26:27], s63, v228
	v_max3_f32 v49, v49, v189, v190
	s_nop 0
	v_cndmask_b32_e64 v55, v182, v50, s[26:27]
	v_add_u32_e32 v229, v45, v172
	v_max3_f32 v49, v49, v191, v192
	v_mul_f32_e32 v50, v128, v52
	v_mul_f32_e32 v51, v129, v13
	v_max3_f32 v49, v49, v193, v198
	v_sub_f32_e32 v50, v50, v51
	v_cmp_gt_u32_e64 s[26:27], s63, v229
	v_max3_f32 v49, v49, v199, v200
	s_nop 0
	v_cndmask_b32_e64 v52, v182, v50, s[26:27]
	v_add_u32_e32 v230, v45, v173
	v_max3_f32 v49, v49, v201, v202
	v_mul_f32_e32 v50, v130, v53
	v_mul_f32_e32 v51, v131, v13
	v_max3_f32 v49, v49, v186, v187
	v_sub_f32_e32 v50, v50, v51
	v_cmp_gt_u32_e64 s[26:27], s63, v230
	v_max3_f32 v49, v49, v64, v65
	s_nop 0
	v_cndmask_b32_e64 v53, v182, v50, s[26:27]
	v_max3_f32 v49, v49, v62, v63
	v_mul_f32_e32 v50, v132, v46
	v_mul_f32_e32 v51, v133, v13
	v_max3_f32 v49, v49, v60, v61
	v_sub_f32_e32 v46, v50, v51
	s_and_b64 s[22:23], s[10:11], s[22:23]
	v_max3_f32 v49, v49, v58, v59
	v_cndmask_b32_e64 v50, v182, v46, s[22:23]
	v_max3_f32 v49, v49, v56, v57
	v_mul_f32_e32 v46, v134, v47
	v_mul_f32_e32 v47, v135, v13
	v_max3_f32 v49, v49, v54, v55
	v_sub_f32_e32 v46, v46, v47
	s_and_b64 s[20:21], s[12:13], s[20:21]
	v_max3_f32 v49, v49, v52, v53
	v_cndmask_b32_e64 v51, v182, v46, s[20:21]
	v_max3_f32 v203, v49, v50, v51
	v_mov_b32_e32 v49, v13
	v_pk_mul_f32 v[46:47], v[48:49], v[136:137]
	s_and_b64 vcc, s[14:15], vcc
	v_sub_f32_e32 v46, v46, v47
	v_and_b32_e32 v206, 64, v183
	v_cndmask_b32_e32 v47, v182, v46, vcc
	v_fma_f32 v12, -v13, v178, v12
	s_and_b64 vcc, s[16:17], s[18:19]
	v_xor_b32_e32 v46, 16, v183
	v_add_u32_e32 v48, 64, v206
	v_cndmask_b32_e32 v12, v182, v12, vcc
	v_cmp_lt_i32_e32 vcc, v46, v48
	v_max3_f32 v13, v203, v47, v12
	s_nop 0
	v_cndmask_b32_e32 v46, v183, v46, vcc
	v_lshlrev_b32_e32 v203, 2, v46
	ds_bpermute_b32 v46, v203, v13
	s_waitcnt lgkmcnt(0)
; __device__ __forceinline__ unsigned cvtpk(float lo, float hi) { const f32v2_t v = {lo, hi}; const bf16v2_t b = __builtin_convertvector(v, bf16v2_t); return __builtin_bit_cast(unsigned, b); }
; __device__ __forceinline__ v4i16_t lds_tr16(const bf16_t* p) { return __builtin_amdgcn_ds_read_tr16_b64_v4i16((LAS v4i16_t*)p); }
; __device__ void phase_attn(const Params& p, unsigned char* smem, int wave) {
;     ...
;         mx = fmaxf(mx, __shfl_xor(mx, 16)); mx = fmaxf(mx, __shfl_xor(mx, 32));
;         float den = 0.f;
; #pragma unroll
;         for (int kt = 0; kt < 9; ++kt)
; #pragma unroll
;             for (int j = 0; j < 4; ++j) { const float pv = __builtin_amdgcn_exp2f(sc[kt][j] - mx); sc[kt][j] = pv; den += pv; }
;         sc[9] = (f32x4){0.f, 0.f, 0.f, 0.f};
;         den += __shfl_xor(den, 16); den += __shfl_xor(den, 32);
;         f32x4 oacc[4];
; #pragma unroll
;         for (int et = 0; et < 4; ++et) oacc[et] = (f32x4){0.f, 0.f, 0.f, 0.f};
; #pragma unroll
;         for (int ks = 0; ks < 5; ++ks) {
;             u32x4 pu; pu.x = cvtpk(sc[2 * ks][0], sc[2 * ks][1]); pu.y = cvtpk(sc[2 * ks][2], sc[2 * ks][3]); pu.z = cvtpk(sc[2 * ks + 1][0], sc[2 * ks + 1][1]); pu.w = cvtpk(sc[2 * ks + 1][2], sc[2 * ks + 1][3]);
;             const bf16x8 pf = __builtin_bit_cast(bf16x8, pu);
;             const bf16_t* vrow = Vs + (16 * w4 + 32 * ks + 4 * gq + (ql >> 2)) * ATT_LD + 4 * (ql & 3);
; #pragma unroll
;             for (int et = 0; et < 4; ++et) {
;                 const v4i16_t t0 = lds_tr16(vrow + 16 * et);
;                 v4i16_t t1 = (v4i16_t){0, 0, 0, 0};
;                 if (ks < 4) t1 = lds_tr16(vrow + 16 * ATT_LD + 16 * et);
;                 const bf16x8 vf = __builtin_shufflevector(t0, t1, 0, 1, 2, 3, 4, 5, 6, 7);
;                 oacc[et] = __builtin_amdgcn_mfma_f32_16x16x32_bf16(pf, vf, oacc[et], 0, 0, 0); }
	v_max_f32_e32 v46, v46, v46
	v_max_f32_e32 v13, v13, v46
	v_xor_b32_e32 v46, 32, v183
	v_cmp_lt_i32_e32 vcc, v46, v48
	s_nop 1
	v_cndmask_b32_e32 v46, v183, v46, vcc
	v_lshlrev_b32_e32 v204, 2, v46
	ds_bpermute_b32 v46, v204, v13
	s_waitcnt lgkmcnt(0)
	v_max_f32_e32 v46, v46, v46
	v_max_f32_e32 v46, v13, v46
	v_sub_f32_e32 v13, v194, v46
	v_exp_f32_e32 v13, v13
	v_sub_f32_e32 v49, v195, v46
	v_exp_f32_e32 v49, v49
	v_sub_f32_e32 v194, v196, v46
	v_exp_f32_e32 v194, v194
	v_sub_f32_e32 v195, v197, v46
	v_exp_f32_e32 v195, v195
	v_sub_f32_e32 v14, v14, v46
	v_add_f32_e32 v48, 0, v13
	v_exp_f32_e32 v14, v14
	v_sub_f32_e32 v188, v188, v46
	v_add_f32_e32 v48, v49, v48
	v_exp_f32_e32 v188, v188
	v_sub_f32_e32 v189, v189, v46
	v_add_f32_e32 v48, v194, v48
	v_exp_f32_e32 v189, v189
	v_sub_f32_e32 v190, v190, v46
	v_add_f32_e32 v48, v195, v48
	v_exp_f32_e32 v190, v190
	v_sub_f32_e32 v191, v191, v46
	v_add_f32_e32 v48, v14, v48
	v_exp_f32_e32 v191, v191
	v_sub_f32_e32 v192, v192, v46
	v_add_f32_e32 v48, v188, v48
	v_exp_f32_e32 v192, v192
	v_sub_f32_e32 v193, v193, v46
	v_add_f32_e32 v48, v189, v48
	v_exp_f32_e32 v193, v193
	v_sub_f32_e32 v196, v198, v46
	v_add_f32_e32 v48, v190, v48
	v_exp_f32_e32 v196, v196
	v_sub_f32_e32 v197, v199, v46
	v_add_f32_e32 v48, v191, v48
	v_exp_f32_e32 v197, v197
	v_sub_f32_e32 v198, v200, v46
	v_add_f32_e32 v48, v192, v48
	v_exp_f32_e32 v198, v198
	v_sub_f32_e32 v199, v201, v46
	v_add_f32_e32 v48, v193, v48
	v_exp_f32_e32 v199, v199
	v_sub_f32_e32 v200, v202, v46
	v_add_f32_e32 v48, v196, v48
	v_exp_f32_e32 v200, v200
	v_sub_f32_e32 v186, v186, v46
	v_add_f32_e32 v48, v197, v48
	v_exp_f32_e32 v207, v186
	v_sub_f32_e32 v186, v187, v46
	v_add_f32_e32 v48, v198, v48
	v_exp_f32_e32 v208, v186
	v_sub_f32_e32 v64, v64, v46
	v_add_f32_e32 v48, v199, v48
	v_exp_f32_e32 v64, v64
	v_sub_f32_e32 v65, v65, v46
	v_add_f32_e32 v48, v200, v48
	v_exp_f32_e32 v65, v65
	v_sub_f32_e32 v62, v62, v46
	v_add_f32_e32 v48, v207, v48
	v_exp_f32_e32 v209, v62
	v_sub_f32_e32 v62, v63, v46
	v_add_f32_e32 v48, v208, v48
	v_exp_f32_e32 v210, v62
	v_sub_f32_e32 v60, v60, v46
	v_add_f32_e32 v48, v64, v48
	v_exp_f32_e32 v211, v60
	v_sub_f32_e32 v60, v61, v46
	v_add_f32_e32 v48, v65, v48
	v_exp_f32_e32 v212, v60
	v_sub_f32_e32 v58, v58, v46
	v_add_f32_e32 v48, v209, v48
	v_exp_f32_e32 v213, v58
	v_sub_f32_e32 v58, v59, v46
	v_add_f32_e32 v48, v210, v48
	v_exp_f32_e32 v214, v58
	v_sub_f32_e32 v56, v56, v46
	v_add_f32_e32 v48, v211, v48
	v_exp_f32_e32 v215, v56
	v_sub_f32_e32 v56, v57, v46
	v_add_f32_e32 v48, v212, v48
	v_exp_f32_e32 v216, v56
	v_sub_f32_e32 v54, v54, v46
	v_add_f32_e32 v48, v213, v48
	v_exp_f32_e32 v217, v54
	v_sub_f32_e32 v54, v55, v46
	v_add_f32_e32 v48, v214, v48
	v_exp_f32_e32 v218, v54
	v_sub_f32_e32 v52, v52, v46
	v_add_f32_e32 v48, v215, v48
	v_exp_f32_e32 v219, v52
	v_sub_f32_e32 v52, v53, v46
	v_add_f32_e32 v48, v216, v48
	v_exp_f32_e32 v220, v52
	v_sub_f32_e32 v50, v50, v46
	v_add_f32_e32 v48, v217, v48
	v_exp_f32_e32 v221, v50
	v_add_f32_e32 v48, v218, v48
	v_add_f32_e32 v48, v219, v48
	v_add_f32_e32 v48, v220, v48
	v_add_f32_e32 v201, v221, v48
	v_sub_f32_e32 v48, v51, v46
	v_exp_f32_e32 v222, v48
	v_sub_f32_e32 v47, v47, v46
	v_cvt_pk_bf16_f32 v48, v13, v49
	v_exp_f32_e32 v13, v47
	v_sub_f32_e32 v12, v12, v46
	v_cvt_pk_bf16_f32 v50, v14, v188
	v_exp_f32_e32 v14, v12
	v_add_f32_e32 v12, v222, v201
	v_add_f32_e32 v12, v13, v12
	v_cvt_pk_bf16_f32 v49, v194, v195
	v_add_f32_e32 v12, v14, v12
	ds_bpermute_b32 v47, v203, v12
	v_cvt_pk_bf16_f32 v51, v189, v190
	ds_read_b64_tr_b16 v[54:55], v179 offset:57600
	ds_read_b64_tr_b16 v[52:53], v179 offset:55296
	ds_read_b64_tr_b16 v[56:57], v179 offset:55328
	ds_read_b64_tr_b16 v[60:61], v179 offset:55360
	ds_read_b64_tr_b16 v[186:187], v179 offset:55392
	ds_read_b64_tr_b16 v[58:59], v179 offset:57632
	ds_read_b64_tr_b16 v[62:63], v179 offset:57664
	ds_read_b64_tr_b16 v[188:189], v179 offset:57696
	v_cvt_pk_bf16_f32 v248, v191, v192
	v_cvt_pk_bf16_f32 v249, v193, v196
	v_cvt_pk_bf16_f32 v250, v197, v198
	v_cvt_pk_bf16_f32 v251, v199, v200
	ds_read_b64_tr_b16 v[234:235], v179 offset:62208
	ds_read_b64_tr_b16 v[232:233], v179 offset:59904
	ds_read_b64_tr_b16 v[236:237], v179 offset:59936
	ds_read_b64_tr_b16 v[240:241], v179 offset:59968
	ds_read_b64_tr_b16 v[244:245], v179 offset:60000
	ds_read_b64_tr_b16 v[238:239], v179 offset:62240
	s_waitcnt lgkmcnt(12)
	v_mfma_f32_16x16x32_bf16 v[52:55], v[48:51], v[52:55], 0
	ds_read_b64_tr_b16 v[242:243], v179 offset:62272
	ds_read_b64_tr_b16 v[246:247], v179 offset:62304
	v_add_f32_e32 v47, v12, v47
	ds_bpermute_b32 v223, v204, v47
	s_waitcnt lgkmcnt(11)
	v_mfma_f32_16x16x32_bf16 v[56:59], v[48:51], v[56:59], 0
	s_waitcnt lgkmcnt(10)
	v_mfma_f32_16x16x32_bf16 v[60:63], v[48:51], v[60:63], 0
	s_waitcnt lgkmcnt(9)
	v_mfma_f32_16x16x32_bf16 v[48:51], v[48:51], v[186:189], 0
	v_cvt_pk_bf16_f32 v186, v207, v208
	v_cvt_pk_bf16_f32 v187, v64, v65
	v_cvt_pk_bf16_f32 v188, v209, v210
	v_cvt_pk_bf16_f32 v189, v211, v212
	ds_read_b64_tr_b16 v[192:193], v180 offset:11520
	ds_read_b64_tr_b16 v[190:191], v179 offset:64512
	ds_read_b64_tr_b16 v[194:195], v179 offset:64544
	ds_read_b64_tr_b16 v[198:199], v179 offset:64576
	ds_read_b64_tr_b16 v[202:203], v179 offset:64608
	ds_read_b64_tr_b16 v[196:197], v180 offset:11552
	s_waitcnt lgkmcnt(13)
	v_mfma_f32_16x16x32_bf16 v[52:55], v[248:251], v[232:235], v[52:55]
	ds_read_b64_tr_b16 v[200:201], v180 offset:11584
	ds_read_b64_tr_b16 v[204:205], v180 offset:11616
	s_waitcnt lgkmcnt(11)
	v_mfma_f32_16x16x32_bf16 v[56:59], v[248:251], v[236:239], v[56:59]
	s_waitcnt lgkmcnt(10)
; __device__ __forceinline__ unsigned cvtpk(float lo, float hi) { const f32v2_t v = {lo, hi}; const bf16v2_t b = __builtin_convertvector(v, bf16v2_t); return __builtin_bit_cast(unsigned, b); }
; __device__ __forceinline__ bf16_t f2bf(float f) { return (bf16_t)cvtpk(f, 0.f); }
; __device__ __forceinline__ v4i16_t lds_tr16(const bf16_t* p) { return __builtin_amdgcn_ds_read_tr16_b64_v4i16((LAS v4i16_t*)p); }
; __device__ void phase_attn(const Params& p, unsigned char* smem, int wave) {
;     ...
;         for (int ks = 0; ks < 5; ++ks) {
;             u32x4 pu; pu.x = cvtpk(sc[2 * ks][0], sc[2 * ks][1]); pu.y = cvtpk(sc[2 * ks][2], sc[2 * ks][3]); pu.z = cvtpk(sc[2 * ks + 1][0], sc[2 * ks + 1][1]); pu.w = cvtpk(sc[2 * ks + 1][2], sc[2 * ks + 1][3]);
;             const bf16x8 pf = __builtin_bit_cast(bf16x8, pu);
;             const bf16_t* vrow = Vs + (16 * w4 + 32 * ks + 4 * gq + (ql >> 2)) * ATT_LD + 4 * (ql & 3);
; #pragma unroll
;             for (int et = 0; et < 4; ++et) {
;                 const v4i16_t t0 = lds_tr16(vrow + 16 * et);
;                 v4i16_t t1 = (v4i16_t){0, 0, 0, 0};
;                 if (ks < 4) t1 = lds_tr16(vrow + 16 * ATT_LD + 16 * et);
;                 const bf16x8 vf = __builtin_shufflevector(t0, t1, 0, 1, 2, 3, 4, 5, 6, 7);
;                 oacc[et] = __builtin_amdgcn_mfma_f32_16x16x32_bf16(pf, vf, oacc[et], 0, 0, 0); }
;             __builtin_amdgcn_sched_barrier(0);
;         }
; #pragma unroll
;         for (int j = 0; j < 4; ++j) { const float dq = __shfl(den, 4 * gq + j); const float inv = __builtin_amdgcn_rcpf(dq);
;             const int tok = gbase + (i0 + 16 * w4 + 4 * gq + j) * d + res;
; #pragma unroll
;             for (int et = 0; et < 4; ++et) ato[(size_t)tok * 512 + h * 64 + 16 * et + ql] = f2bf(oacc[et][j] * inv); }
;         if (gq == 0) { const int tok = gbase + qi * d + res; lse[((size_t)br * NTOK + tok) * 8 + h] = mx * 0.6931471805599453f + __logf(den); }
	v_mfma_f32_16x16x32_bf16 v[60:63], v[248:251], v[240:243], v[60:63]
	s_waitcnt lgkmcnt(9)
	v_mfma_f32_16x16x32_bf16 v[48:51], v[248:251], v[244:247], v[48:51]
	v_cvt_pk_bf16_f32 v248, v213, v214
	v_cvt_pk_bf16_f32 v249, v215, v216
	v_cvt_pk_bf16_f32 v250, v217, v218
	v_cvt_pk_bf16_f32 v251, v219, v220
	ds_read_b64_tr_b16 v[234:235], v180 offset:16128
	ds_read_b64_tr_b16 v[232:233], v180 offset:13824
	ds_read_b64_tr_b16 v[236:237], v180 offset:13856
	ds_read_b64_tr_b16 v[240:241], v180 offset:13888
	ds_read_b64_tr_b16 v[244:245], v180 offset:13920
	ds_read_b64_tr_b16 v[238:239], v180 offset:16160
	s_waitcnt lgkmcnt(12)
	v_mfma_f32_16x16x32_bf16 v[52:55], v[186:189], v[190:193], v[52:55]
	ds_read_b64_tr_b16 v[242:243], v180 offset:16192
	ds_read_b64_tr_b16 v[246:247], v180 offset:16224
	s_waitcnt lgkmcnt(10)
	v_mfma_f32_16x16x32_bf16 v[56:59], v[186:189], v[194:197], v[56:59]
	s_waitcnt lgkmcnt(9)
	v_mfma_f32_16x16x32_bf16 v[60:63], v[186:189], v[198:201], v[60:63]
	s_waitcnt lgkmcnt(8)
	v_mfma_f32_16x16x32_bf16 v[48:51], v[186:189], v[202:205], v[48:51]
	v_cvt_pk_bf16_f32 v12, v221, v222
	v_cvt_pk_bf16_f32 v13, v13, v14
	v_mov_b32_e32 v14, v15
	ds_read_b64_tr_b16 v[186:187], v180 offset:18432
	ds_read_b64_tr_b16 v[190:191], v180 offset:18464
	ds_read_b64_tr_b16 v[194:195], v180 offset:18496
	ds_read_b64_tr_b16 v[198:199], v180 offset:18528
	v_mov_b32_e32 v188, v15
	v_mov_b32_e32 v189, v15
	v_mov_b32_e32 v192, v15
	v_mov_b32_e32 v193, v15
	v_mov_b32_e32 v196, v15
	v_mov_b32_e32 v197, v15
	v_mov_b32_e32 v200, v15
	v_mov_b32_e32 v201, v15
	s_waitcnt lgkmcnt(10)
	v_mfma_f32_16x16x32_bf16 v[52:55], v[248:251], v[232:235], v[52:55]
	s_waitcnt lgkmcnt(6)
	v_mfma_f32_16x16x32_bf16 v[56:59], v[248:251], v[236:239], v[56:59]
	s_waitcnt lgkmcnt(5)
	v_mfma_f32_16x16x32_bf16 v[60:63], v[248:251], v[240:243], v[60:63]
	s_waitcnt lgkmcnt(4)
	v_mfma_f32_16x16x32_bf16 v[48:51], v[248:251], v[244:247], v[48:51]
	s_waitcnt lgkmcnt(3)
	v_mfma_f32_16x16x32_bf16 v[52:55], v[12:15], v[186:189], v[52:55]
	s_waitcnt lgkmcnt(2)
	v_mfma_f32_16x16x32_bf16 v[56:59], v[12:15], v[190:193], v[56:59]
	s_waitcnt lgkmcnt(1)
	v_mfma_f32_16x16x32_bf16 v[60:63], v[12:15], v[194:197], v[60:63]
	s_waitcnt lgkmcnt(0)
	v_mfma_f32_16x16x32_bf16 v[48:51], v[12:15], v[198:201], v[48:51]
	v_or_b32_e32 v14, v206, v141
	v_add_f32_e32 v12, v47, v223
	v_lshlrev_b32_e32 v14, 2, v14
	ds_bpermute_b32 v47, v14, v12
	s_add_i32 s62, s62, s61
	s_lshl_b32 s18, s57, 7
	s_add_u32 s18, s59, s18
	v_or_b32_e32 v13, v139, v141
	s_addc_u32 s19, s60, 0
	v_mov_b32_e32 v139, v15
	s_waitcnt lgkmcnt(0)
	v_rcp_f32_e32 v47, v47
	v_lshl_add_u64 v[64:65], s[18:19], 0, v[138:139]
	v_lshlrev_b32_e32 v139, s58, v13
	v_add_u32_e32 v186, s62, v139
	v_ashrrev_i32_e32 v187, 31, v186
	v_lshlrev_b64 v[186:187], 10, v[186:187]
	v_mul_f32_e32 v52, v52, v47
	v_lshl_add_u64 v[186:187], v[64:65], 0, v[186:187]
	v_cvt_pk_bf16_f32 v52, v52, s0
	global_store_short v[186:187], v52, off
	v_mul_f32_e32 v52, v56, v47
	ds_bpermute_b32 v56, v14, v12 offset:4
	v_cvt_pk_bf16_f32 v52, v52, s0
	global_store_short v[186:187], v52, off offset:32
	v_mul_f32_e32 v52, v60, v47
	v_mul_f32_e32 v47, v48, v47
	v_cvt_pk_bf16_f32 v47, v47, s0
	global_store_short v[186:187], v47, off offset:96
	s_waitcnt lgkmcnt(0)
	v_rcp_f32_e32 v47, v56
	v_or_b32_e32 v48, 1, v13
	v_cvt_pk_bf16_f32 v52, v52, s0
	v_lshlrev_b32_e32 v48, s58, v48
	global_store_short v[186:187], v52, off offset:64
	v_add_u32_e32 v186, s62, v48
	v_ashrrev_i32_e32 v187, 31, v186
	v_lshlrev_b64 v[186:187], 10, v[186:187]
	v_mul_f32_e32 v48, v53, v47
	v_lshl_add_u64 v[186:187], v[64:65], 0, v[186:187]
	v_cvt_pk_bf16_f32 v48, v48, s0
	ds_bpermute_b32 v52, v14, v12 offset:8
	global_store_short v[186:187], v48, off
	v_mul_f32_e32 v48, v57, v47
	v_cvt_pk_bf16_f32 v48, v48, s0
	global_store_short v[186:187], v48, off offset:32
	v_mul_f32_e32 v48, v61, v47
	v_mul_f32_e32 v47, v49, v47
	v_cvt_pk_bf16_f32 v48, v48, s0
	v_cvt_pk_bf16_f32 v47, v47, s0
	global_store_short v[186:187], v48, off offset:64
	global_store_short v[186:187], v47, off offset:96
	s_waitcnt lgkmcnt(0)
	v_rcp_f32_e32 v47, v52
	v_or_b32_e32 v48, 2, v13
	v_lshlrev_b32_e32 v48, s58, v48
	v_add_u32_e32 v48, s62, v48
	v_or_b32_e32 v14, 12, v14
	v_ashrrev_i32_e32 v49, 31, v48
	ds_bpermute_b32 v14, v14, v12
	v_lshlrev_b64 v[48:49], 10, v[48:49]
	v_mul_f32_e32 v52, v54, v47
	v_lshl_add_u64 v[48:49], v[64:65], 0, v[48:49]
	v_cvt_pk_bf16_f32 v52, v52, s0
	global_store_short v[48:49], v52, off
	v_mul_f32_e32 v52, v58, v47
	v_cvt_pk_bf16_f32 v52, v52, s0
	global_store_short v[48:49], v52, off offset:32
	v_mul_f32_e32 v52, v62, v47
	v_mul_f32_e32 v47, v50, v47
	s_waitcnt lgkmcnt(0)
	v_rcp_f32_e32 v14, v14
	v_or_b32_e32 v13, 3, v13
	v_cvt_pk_bf16_f32 v52, v52, s0
	v_cvt_pk_bf16_f32 v47, v47, s0
	v_lshlrev_b32_e32 v13, s58, v13
	global_store_short v[48:49], v52, off offset:64
	global_store_short v[48:49], v47, off offset:96
	v_add_u32_e32 v48, s62, v13
	v_ashrrev_i32_e32 v49, 31, v48
	v_lshlrev_b64 v[48:49], 10, v[48:49]
	v_mul_f32_e32 v13, v55, v14
	v_lshl_add_u64 v[48:49], v[64:65], 0, v[48:49]
	v_cvt_pk_bf16_f32 v13, v13, s0
	global_store_short v[48:49], v13, off
	v_mul_f32_e32 v13, v59, v14
	v_cvt_pk_bf16_f32 v13, v13, s0
	global_store_short v[48:49], v13, off offset:32
	v_mul_f32_e32 v13, v63, v14
	v_cvt_pk_bf16_f32 v13, v13, s0
	global_store_short v[48:49], v13, off offset:64
	v_mul_f32_e32 v13, v51, v14
	v_cvt_pk_bf16_f32 v13, v13, s0
	global_store_short v[48:49], v13, off offset:96
	s_and_saveexec_b64 s[20:21], s[0:1]
	s_cbranch_execz .LBB0_719
	v_cmp_gt_f32_e32 vcc, s53, v12
	s_nop 1
	v_cndmask_b32_e64 v13, 0, 32, vcc
	v_ldexp_f32 v12, v12, v13
	v_log_f32_e32 v13, v12
	v_lshlrev_b32_e32 v12, s58, v45
	v_add_u32_e32 v12, s62, v12
	v_mul_f32_e32 v14, 0x3f317217, v13
	v_fma_f32 v14, v13, s54, -v14
	v_fmac_f32_e32 v14, 0x3377d1cf, v13
	v_fmac_f32_e32 v14, 0x3f317217, v13
	v_cmp_lt_f32_e64 s[18:19], |v13|, s55
	s_nop 1
	v_cndmask_b32_e64 v13, v13, v14, s[18:19]
	v_cndmask_b32_e32 v14, 0, v184, vcc
	v_sub_f32_e32 v14, v13, v14
	v_ashrrev_i32_e32 v13, 31, v12
	v_mad_i64_i32 v[12:13], s[18:19], s42, v185, v[12:13]
	v_lshlrev_b64 v[12:13], 5, v[12:13]
	v_lshl_add_u64 v[12:13], s[40:41], 0, v[12:13]
	s_lshl_b32 s42, s57, 2
	v_fmac_f32_e32 v14, 0x3f317218, v46
	v_lshl_add_u64 v[12:13], v[12:13], 0, s[42:43]
	global_store_dword v[12:13], v14, off
	s_branch .LBB0_719
